# ssd staging: transposed 16-bit LDS stores paired across adjacent lanes (dpp+perm -> ds_write_b32, 48->24 stores); plus p7/p10/p12 epilogue load hoists
# baseline (speedup 1.0000x reference)
; #define PG8_LAS __attribute__((address_space(3)))
; __device__ __forceinline__ void phase_ssd_mfma(const Params& p, unsigned char* smem) {
;     using pg8::bf16x8;
;     const int tid = threadIdx.x, lane = tid & 63, wave = __builtin_amdgcn_readfirstlane(tid >> 6), fr = lane & 15, fq = lane >> 4;
;     PG8_LAS unsigned char* L = (PG8_LAS unsigned char*)smem;
;     PG8_LAS float* scs = (PG8_LAS float*)(L + SS_CS); PG8_LAS float* sdt = (PG8_LAS float*)(L + SS_DT);
;     const bf16_t* xcl = (const bf16_t*)p.out; const bf16_t* xcc = (const bf16_t*)(p.ws + OFF_XC); const float* DT = (const float*)(p.ws + OFF_DT);
;     ...
;     for (int item = blockIdx.x; item < 256; item += gridDim.x) {
;         const int xcd = item & 7, slot = item >> 3, gid = xcd * 4 + (slot >> 3), mem = slot & 7;
;         const int b = gid >> 3, g = gid & 7, dir = mem >> 2, h = g * 4 + (mem & 3);
;         const float Ah = -expf(p.in[11][dir * 32 + h]), dsk = p.in[12][dir * 32 + h];
;         bf16_t* Y = (bf16_t*)(p.ws + (dir ? OFF_YB : OFF_YF));
;         f32x4 H[4];
; #pragma unroll
;         for (int j = 0; j < 4; ++j) H[j] = (f32x4){0.f, 0.f, 0.f, 0.f};
;         const int hi_half = wave & 1, sm = lane + 64 * hi_half, q4 = wave >> 1;
.LBB0_419:
	s_cmp_lt_i32 s86, 6
	s_cselect_b64 s[2:3], -1, 0
	s_and_b64 s[2:3], s[2:3], s[0:1]
	s_andn2_b64 vcc, exec, s[2:3]
	v_writelane_b32 v235, s70, 53
	s_cbranch_vccnz .LBB0_476
	s_cmpk_gt_i32 s88, 0xff
	v_readfirstlane_b32 s0, v154
	s_cbranch_scc1 .LBB0_476
	v_writelane_b32 v235, s2, 54
	s_mov_b64 s[44:45], s[80:81]
	v_and_b32_e32 v1, 63, v154
	v_writelane_b32 v235, s3, 55
	v_writelane_b32 v235, s78, 56
	s_add_u32 s2, s84, 0x490000
	s_addc_u32 s3, s85, 0
	v_writelane_b32 v235, s79, 57
	v_writelane_b32 v235, s2, 58
	s_mov_b64 s[46:47], s[82:83]
	s_mov_b64 s[48:49], s[84:85]
	v_writelane_b32 v235, s3, 59
	s_add_u32 s2, s84, 0x50000
	s_addc_u32 s3, s85, 0
	v_writelane_b32 v235, s2, 60
	s_lshr_b32 s1, s0, 6
	s_mov_b64 s[50:51], s[86:87]
	v_writelane_b32 v235, s3, 61
	s_bfe_u32 s2, s0, 0x10006
	s_lshr_b32 s3, s0, 7
	s_cmp_eq_u32 s2, 0
	s_cselect_b64 s[80:81], -1, 0
	s_lshl_b32 s5, s3, 3
	v_or_b32_e32 v140, 64, v1
	s_cmp_lt_u32 s0, 64
	v_and_b32_e32 v3, 15, v154
	v_lshl_or_b32 v2, s2, 6, v1
	s_cselect_b64 s[92:93], -1, 0
	s_add_i32 s25, 0, 0x22200
	v_lshlrev_b32_e32 v4, 2, v140
	s_add_i32 s26, 0, 0x22000
	s_movk_i32 s28, 0x110
	v_mov_b32_e32 v14, 0x1100
	s_waitcnt lgkmcnt(0)
; __device__ __forceinline__ void phase_ssd_mfma(const Params& p, unsigned char* smem) {
;     using pg8::bf16x8;
;     const int tid = threadIdx.x, lane = tid & 63, wave = __builtin_amdgcn_readfirstlane(tid >> 6), fr = lane & 15, fq = lane >> 4;
;     PG8_LAS unsigned char* L = (PG8_LAS unsigned char*)smem;
;     PG8_LAS float* scs = (PG8_LAS float*)(L + SS_CS); PG8_LAS float* sdt = (PG8_LAS float*)(L + SS_DT);
;     const bf16_t* xcl = (const bf16_t*)p.out; const bf16_t* xcc = (const bf16_t*)(p.ws + OFF_XC); const float* DT = (const float*)(p.ws + OFF_DT);
;     ...
;     for (int item = blockIdx.x; item < 256; item += gridDim.x) {
;         const int xcd = item & 7, slot = item >> 3, gid = xcd * 4 + (slot >> 3), mem = slot & 7;
;         const int b = gid >> 3, g = gid & 7, dir = mem >> 2, h = g * 4 + (mem & 3);
;         const float Ah = -expf(p.in[11][dir * 32 + h]), dsk = p.in[12][dir * 32 + h];
;         bf16_t* Y = (bf16_t*)(p.ws + (dir ? OFF_YB : OFF_YF));
;         f32x4 H[4];
; #pragma unroll
;         for (int j = 0; j < 4; ++j) H[j] = (f32x4){0.f, 0.f, 0.f, 0.f};
;         const int hi_half = wave & 1, sm = lane + 64 * hi_half, q4 = wave >> 1;
;         float dt_lo, dt_hi; u32x4 xv[2], bv[4], cv[4];
;     ...
;             for (int j = 0; j < 2; ++j) { const int p0 = 8 * (q4 + 4 * j); const u32x4 v = xv[j];
;                 PG8_LAS unsigned char* d = L + SS_XT + p0 * SS_LD + sm * 2;
;                 *(PG8_LAS unsigned short*)(d + 0 * SS_LD) = (unsigned short)(v.x & 0xffffu); *(PG8_LAS unsigned short*)(d + 1 * SS_LD) = (unsigned short)(v.x >> 16);
;                 *(PG8_LAS unsigned short*)(d + 2 * SS_LD) = (unsigned short)(v.y & 0xffffu); *(PG8_LAS unsigned short*)(d + 3 * SS_LD) = (unsigned short)(v.y >> 16);
;                 *(PG8_LAS unsigned short*)(d + 4 * SS_LD) = (unsigned short)(v.z & 0xffffu); *(PG8_LAS unsigned short*)(d + 5 * SS_LD) = (unsigned short)(v.z >> 16);
;                 *(PG8_LAS unsigned short*)(d + 6 * SS_LD) = (unsigned short)(v.w & 0xffffu); *(PG8_LAS unsigned short*)(d + 7 * SS_LD) = (unsigned short)(v.w >> 16); }
; #pragma unroll
;             for (int j = 0; j < 4; ++j) { const int n0 = 8 * (q4 + 4 * j); const u32x4 v = bv[j];
;                 if (!isctx) *(PG8_LAS u32x4*)(L + SS_B + sm * SS_LD + n0 * 2) = v;
;                 float f[8]; unpack8(v, f);
;                 PG8_LAS unsigned char* d = L + SS_BT + n0 * SS_LD + sm * 2;
	v_bfe_u32 v5, v154, 4, 2
	v_add_u32_e32 v141, s25, v4
	v_add_u32_e32 v143, s26, v4
	v_lshlrev_b32_e32 v4, 1, v2
	s_add_i32 s27, 0, 0x19800
	s_add_i32 s2, 0, 0x11000
	v_mad_u32_u24 v161, v3, s28, v14
	v_mov_b32_e32 v14, 0x2200
	v_add_u32_e32 v145, s27, v4
	v_add_u32_e32 v146, s2, v4
	v_and_b32_e32 v236, 1, v154
	v_mov_b32_e32 v239, 0xfdfe0606
	v_mul_lo_u32 v239, v236, v239
	v_add_u32_e32 v239, 0x5040100, v239
	v_mul_u32_u24_e32 v236, 0x10e, v236
	v_add_u32_e32 v237, v145, v236
	v_add_u32_e32 v238, v146, v236
	v_lshlrev_b32_e32 v4, 2, v5
	v_mad_u32_u24 v162, v3, s28, v14
	v_mov_b32_e32 v14, 0x3300
	v_lshl_or_b32 v9, s1, 4, v3
	v_mad_u32_u24 v163, v3, s28, v14
	v_or_b32_e32 v14, 16, v4
	v_cmp_gt_u32_e64 s[6:7], v14, v9
	v_or_b32_e32 v14, 17, v4
	v_cmp_gt_u32_e64 s[10:11], v14, v9
	v_or_b32_e32 v14, 2, v4
	v_cmp_gt_u32_e64 s[12:13], v14, v9
	v_or_b32_e32 v14, 18, v4
	v_cmp_gt_u32_e64 s[14:15], v14, v9
	v_or_b32_e32 v14, 3, v4
	v_cmp_gt_u32_e64 s[16:17], v14, v9
	v_or_b32_e32 v14, 19, v4
	v_cmp_gt_u32_e64 s[18:19], v14, v9
	v_or_b32_e32 v14, 32, v4
	v_lshlrev_b32_e32 v15, 2, v14
	v_add_u32_e32 v167, s26, v15
	v_add_u32_e32 v168, s25, v15
	v_or_b32_e32 v15, 48, v4
	v_cmp_gt_u32_e64 s[68:69], v15, v9
	v_or_b32_e32 v15, 33, v4
	v_cmp_gt_u32_e64 s[78:79], v15, v9
	v_or_b32_e32 v15, 49, v4
	v_writelane_b32 v235, s5, 62
	v_cmp_gt_u32_e64 s[30:31], v15, v9
	v_or_b32_e32 v15, 34, v4
	v_mul_lo_u32 v10, v9, s28
	v_writelane_b32 v235, s30, 63
	v_add_u32_e32 v153, 0, v10
	v_add_u32_e32 v10, s2, v10
	v_writelane_b32 v234, s31, 0
	v_cmp_gt_u32_e64 s[30:31], v15, v9
	v_or_b32_e32 v15, 50, v4
	s_lshl_b32 s1, s1, 5
	v_writelane_b32 v234, s30, 1
	s_add_i32 s2, s5, 32
	s_lshl_b32 s91, s3, 4
	v_writelane_b32 v234, s31, 2
	v_cmp_gt_u32_e64 s[30:31], v15, v9
	v_or_b32_e32 v15, 35, v4
	s_add_i32 s1, s1, 0
	v_writelane_b32 v234, s30, 3
	s_lshl_b32 s20, s2, 1
	s_add_i32 s21, s91, 0x80
	v_writelane_b32 v234, s31, 4
	v_cmp_gt_u32_e64 s[30:31], v15, v9
	v_or_b32_e32 v15, 51, v4
	s_add_i32 s22, s91, 0xc0
	v_writelane_b32 v234, s30, 5
	s_cmpk_gt_u32 s0, 0x7f
	s_cselect_b64 s[94:95], -1, 0
	v_writelane_b32 v234, s31, 6
	v_cmp_gt_u32_e64 s[30:31], v15, v9
	v_or_b32_e32 v15, 64, v4
	v_lshlrev_b32_e32 v16, 2, v15
	v_writelane_b32 v234, s30, 7
	v_add_u32_e32 v169, s26, v16
	v_add_u32_e32 v170, s25, v16
	v_writelane_b32 v234, s31, 8
	v_cmp_gt_u32_e64 s[30:31], v15, v9
	v_or_b32_e32 v16, 0x50, v4
	s_cmpk_gt_u32 s0, 0xff
	v_writelane_b32 v234, s30, 9
	s_cselect_b64 s[96:97], -1, 0
	s_cmpk_gt_u32 s0, 0x17f
	v_writelane_b32 v234, s31, 10
	v_cmp_gt_u32_e64 s[30:31], v16, v9
	v_or_b32_e32 v16, 0x41, v4
	s_movk_i32 s4, 0xff
	v_writelane_b32 v234, s30, 11
	s_mul_i32 s33, s3, 0x880
	s_mul_i32 s90, s2, 0x110
	v_writelane_b32 v234, s31, 12
	v_cmp_gt_u32_e64 s[30:31], v16, v9
	v_or_b32_e32 v16, 0x51, v4
	s_cselect_b64 s[2:3], -1, 0
	v_writelane_b32 v234, s30, 13
	s_cmpk_lt_u32 s0, 0x80
	v_bitop3_b32 v138, v154, s4, 63 bitop3:0x6c
	v_writelane_b32 v234, s31, 14
	v_cmp_gt_u32_e64 s[30:31], v16, v9
	v_or_b32_e32 v16, 0x42, v4
	s_movk_i32 s4, 0xbf
	v_writelane_b32 v234, s30, 15
	s_cselect_b32 s23, 0, 64
	s_cmpk_lt_u32 s0, 0x100
	v_writelane_b32 v234, s31, 16
	v_cmp_gt_u32_e64 s[30:31], v16, v9
	v_or_b32_e32 v16, 0x52, v4
	v_bitop3_b32 v139, v154, s4, 63 bitop3:0x6c
	v_writelane_b32 v234, s30, 17
	v_lshlrev_b32_e32 v6, 2, v1
	v_mad_u32_u24 v147, v2, s28, 0
	v_writelane_b32 v234, s31, 18
	v_cmp_gt_u32_e64 s[30:31], v16, v9
	v_or_b32_e32 v16, 0x43, v4
	v_lshlrev_b32_e32 v2, 4, v154
	v_writelane_b32 v234, s30, 19
	s_movk_i32 s4, 0x7f
	v_and_b32_e32 v155, 48, v154
	v_writelane_b32 v234, s31, 20
	v_cmp_gt_u32_e64 s[30:31], v16, v9
	v_or_b32_e32 v16, 0x53, v4
	s_cselect_b32 s24, 0, 0x80
	v_writelane_b32 v234, s30, 21
	s_cmpk_lt_u32 s0, 0x180
	v_add_u32_e32 v142, s25, v6
	v_writelane_b32 v234, s31, 22
	v_cmp_gt_u32_e64 s[30:31], v16, v9
	v_or_b32_e32 v16, 0x60, v4
	v_lshlrev_b32_e32 v17, 2, v16
	v_writelane_b32 v234, s30, 23
	v_add_u32_e32 v171, s26, v17
	v_add_u32_e32 v172, s25, v17
	v_writelane_b32 v234, s31, 24
	v_cmp_gt_u32_e64 s[30:31], v16, v9
	v_or_b32_e32 v17, 0x70, v4
	v_and_b32_e32 v2, 0xf0, v2
	v_writelane_b32 v234, s30, 25
	v_bitop3_b32 v150, v154, s4, 63 bitop3:0x6c
	s_movk_i32 s4, 0xfbf
	v_writelane_b32 v234, s31, 26
	v_cmp_gt_u32_e64 s[30:31], v17, v9
	v_or_b32_e32 v17, 0x61, v4
	v_cmp_gt_u32_e64 s[58:59], v17, v9
	v_or_b32_e32 v17, 0x71, v4
	v_cmp_gt_u32_e64 s[60:61], v17, v9
	v_or_b32_e32 v17, 0x62, v4
	v_cmp_gt_u32_e64 s[62:63], v17, v9
	v_or_b32_e32 v17, 0x72, v4
	v_mov_b32_e32 v11, s27
	v_add_u32_e32 v166, s25, v155
	v_cmp_gt_u32_e64 s[52:53], v17, v9
	v_or_b32_e32 v17, 0x63, v4
	s_cselect_b32 s25, 0, 0xc0
	s_add_i32 s0, s27, s23
	v_add_u32_e32 v144, s26, v6
	v_lshrrev_b32_e32 v148, 4, v154
	v_add_u32_e32 v6, 0, v2
	v_bitop3_b32 v7, v154, s4, 63 bitop3:0x6c
	v_lshlrev_b32_e32 v2, 3, v154
	v_add_u32_e32 v158, 0, v155
	v_cmp_gt_u32_e64 s[54:55], v17, v9
	v_or_b32_e32 v17, 0x73, v4
	v_mad_u32_u24 v174, v3, s28, v11
	v_add_u32_e32 v176, s0, v155
	s_add_i32 s0, s27, s24
	v_and_b32_e32 v2, 0x78, v2
	v_xor_b32_e32 v8, 0xfff, v148
	v_lshlrev_b32_e32 v159, 3, v5
	v_lshl_add_u32 v12, v9, 1, s27
	v_mul_u32_u24_e32 v13, 0x110, v148
	v_mul_u32_u24_e32 v160, 0x110, v3
	v_mad_u32_u24 v164, v3, s28, v158
	v_cmp_gt_u32_e64 s[66:67], v14, v9
	v_lshlrev_b32_e32 v14, 1, v14
	v_lshlrev_b32_e32 v15, 1, v15
	v_writelane_b32 v234, s30, 27
	v_cmp_gt_u32_e64 s[56:57], v17, v9
	v_lshlrev_b32_e32 v16, 1, v16
	v_mul_u32_u24_e32 v5, 0x440, v5
	v_add_u32_e32 v173, 0x80, v7
	v_add_u32_e32 v3, s27, v161
	v_add_u32_e32 v175, s27, v155
	v_add_u32_e32 v7, s27, v162
	v_add_u32_e32 v11, s27, v163
	v_add_u32_e32 v17, s23, v174
	v_add_u32_e32 v18, s24, v174
	v_add_u32_e32 v19, s25, v174
	v_add_u32_e32 v177, s0, v155
	s_add_i32 s27, s27, s25
	s_movk_i32 s0, 0x107f
	s_mov_b32 s85, 0
	v_or_b32_e32 v149, 0x80, v1
	v_bitop3_b32 v151, v154, 63, v154 bitop3:0xc
	v_or_b32_e32 v152, 0xc0, v1
	v_mov_b32_e32 v123, 0
	v_add_u32_e32 v156, v153, v155
	v_lshl_add_u32 v157, v9, 2, s26
	v_add_u32_e32 v165, s26, v155
	v_cmp_gt_u32_e64 s[4:5], v4, v9
	v_cmp_lt_u32_e64 s[8:9], v4, v9
	v_writelane_b32 v234, s31, 28
	v_add_u32_e32 v178, s27, v155
	v_add3_u32 v179, s1, v159, v160
	v_sub_u32_e32 v180, 0, v148
	v_add_u32_e32 v181, 0xffffff00, v9
	v_sub_u32_e32 v182, 0x10ff, v9
	v_add_u32_e32 v183, 0x80, v8
	v_bitop3_b32 v184, v154, s0, 63 bitop3:0x6c
	s_mov_b64 s[82:83], 0x1000
	s_movk_i32 s26, 0x1000
	v_lshlrev_b32_e32 v124, 1, v4
	v_add_u32_e32 v185, v6, v13
	v_lshlrev_b32_e32 v122, 1, v2
	s_mov_b32 s27, 0x1dc00
	v_add_u32_e32 v186, v153, v14
	v_add_u32_e32 v187, v153, v15
	v_add_u32_e32 v188, v153, v16
	v_add_u32_e32 v189, v10, v155
	v_add_u32_e32 v190, v3, v155
	v_add_u32_e32 v191, v7, v155
	v_add_u32_e32 v192, v11, v155
	v_add_u32_e32 v193, v17, v155
	v_add_u32_e32 v194, v18, v155
	v_add_u32_e32 v195, v19, v155
	v_mov_b32_e32 v196, 0x7f800000
	v_mov_b32_e32 v197, 0x3fb8aa3b
	v_add_u32_e32 v198, v12, v5
	s_mov_b32 s28, s88
	v_writelane_b32 v234, s88, 29
	s_branch .LBB0_423

; #define PG8_LAS __attribute__((address_space(3)))
; __device__ __forceinline__ unsigned pk2(float lo, float hi) { return pg8::cvt_pk_bf16(lo, hi); }
; __device__ __forceinline__ void unpack8(const u32x4 r, float (&o)[8]) { o[0] = bflo(r.x); o[1] = bfhi(r.x); o[2] = bflo(r.y); o[3] = bfhi(r.y); o[4] = bflo(r.z); o[5] = bfhi(r.z); o[6] = bflo(r.w); o[7] = bfhi(r.w); }
; __device__ __forceinline__ void phase_ssd_mfma(const Params& p, unsigned char* smem) {
;     ...
;             for (int j = 0; j < 2; ++j) { const int p0 = 8 * (q4 + 4 * j); const u32x4 v = xv[j];
;                 PG8_LAS unsigned char* d = L + SS_XT + p0 * SS_LD + sm * 2;
;                 *(PG8_LAS unsigned short*)(d + 0 * SS_LD) = (unsigned short)(v.x & 0xffffu); *(PG8_LAS unsigned short*)(d + 1 * SS_LD) = (unsigned short)(v.x >> 16);
;                 *(PG8_LAS unsigned short*)(d + 2 * SS_LD) = (unsigned short)(v.y & 0xffffu); *(PG8_LAS unsigned short*)(d + 3 * SS_LD) = (unsigned short)(v.y >> 16);
;                 *(PG8_LAS unsigned short*)(d + 4 * SS_LD) = (unsigned short)(v.z & 0xffffu); *(PG8_LAS unsigned short*)(d + 5 * SS_LD) = (unsigned short)(v.z >> 16);
;                 *(PG8_LAS unsigned short*)(d + 6 * SS_LD) = (unsigned short)(v.w & 0xffffu); *(PG8_LAS unsigned short*)(d + 7 * SS_LD) = (unsigned short)(v.w >> 16); }
; #pragma unroll
;             for (int j = 0; j < 4; ++j) { const int n0 = 8 * (q4 + 4 * j); const u32x4 v = bv[j];
;                 if (!isctx) *(PG8_LAS u32x4*)(L + SS_B + sm * SS_LD + n0 * 2) = v;
;                 float f[8]; unpack8(v, f);
;                 PG8_LAS unsigned char* d = L + SS_BT + n0 * SS_LD + sm * 2;
; #pragma unroll
;                 for (int e = 0; e < 8; e += 2) { const unsigned w2 = pk2(f[e] * wsc, f[e + 1] * wsc);
;                     *(PG8_LAS unsigned short*)(d + e * SS_LD) = (unsigned short)(w2 & 0xffffu); *(PG8_LAS unsigned short*)(d + (e + 1) * SS_LD) = (unsigned short)(w2 >> 16); } }
.LBB0_428:
	s_cmp_gt_u32 s35, 1
	s_cselect_b64 s[0:1], -1, 0
	v_add_u32_e32 v76, s33, v237
	s_waitcnt vmcnt(5)
	s_nop 1
	v_mov_b32_dpp v240, v34 quad_perm:[1,0,3,2] row_mask:0xf bank_mask:0xf
	v_perm_b32 v240, v240, v34, v239
	ds_write_b32 v76, v240
	s_nop 1
	v_mov_b32_dpp v241, v35 quad_perm:[1,0,3,2] row_mask:0xf bank_mask:0xf
	v_perm_b32 v241, v241, v35, v239
	ds_write_b32 v76, v241 offset:544
	s_nop 1
	v_mov_b32_dpp v242, v36 quad_perm:[1,0,3,2] row_mask:0xf bank_mask:0xf
	v_perm_b32 v242, v242, v36, v239
	ds_write_b32 v76, v242 offset:1088
	s_nop 1
	v_mov_b32_dpp v243, v37 quad_perm:[1,0,3,2] row_mask:0xf bank_mask:0xf
	v_perm_b32 v243, v243, v37, v239
	ds_write_b32 v76, v243 offset:1632
	v_add_u32_e32 v76, s90, v237
	s_and_b64 vcc, exec, s[0:1]
	s_waitcnt vmcnt(4)
	s_nop 1
	v_mov_b32_dpp v240, v38 quad_perm:[1,0,3,2] row_mask:0xf bank_mask:0xf
	v_perm_b32 v240, v240, v38, v239
	ds_write_b32 v76, v240
	s_nop 1
	v_mov_b32_dpp v241, v39 quad_perm:[1,0,3,2] row_mask:0xf bank_mask:0xf
	v_perm_b32 v241, v241, v39, v239
	ds_write_b32 v76, v241 offset:544
	s_nop 1
	v_mov_b32_dpp v242, v40 quad_perm:[1,0,3,2] row_mask:0xf bank_mask:0xf
	v_perm_b32 v242, v242, v40, v239
	ds_write_b32 v76, v242 offset:1088
	s_nop 1
	v_mov_b32_dpp v243, v41 quad_perm:[1,0,3,2] row_mask:0xf bank_mask:0xf
	v_perm_b32 v243, v243, v41, v239
	ds_write_b32 v76, v243 offset:1632
	s_cbranch_vccz .LBB0_430
	v_add_u32_e32 v76, s91, v147
	s_waitcnt vmcnt(1)
	ds_write_b128 v76, v[42:45] offset:34816
.LBB0_430:
	v_cndmask_b32_e64 v74, v75, v74, s[80:81]
	v_sub_f32_e32 v74, s76, v74
	v_mul_f32_e32 v74, 0x3fb8aa3b, v74
	v_exp_f32_e32 v74, v74
	v_cndmask_b32_e64 v75, v202, v201, s[80:81]
	s_waitcnt vmcnt(1)
	v_lshlrev_b32_e32 v76, 16, v42
	v_and_b32_e32 v77, 0xffff0000, v42
	v_mul_f32_e32 v74, v75, v74
	v_lshlrev_b32_e32 v75, 16, v43
	v_mul_f32_e32 v76, v74, v76
	v_mul_f32_e32 v77, v74, v77
	v_and_b32_e32 v78, 0xffff0000, v43
	v_cvt_pk_bf16_f32 v76, v76, v77
	v_add_u32_e32 v77, s33, v238
	v_mul_f32_e32 v75, v74, v75
	v_lshlrev_b32_e32 v79, 16, v44
	s_nop 1
	v_mov_b32_dpp v240, v76 quad_perm:[1,0,3,2] row_mask:0xf bank_mask:0xf
	v_perm_b32 v240, v240, v76, v239
	ds_write_b32 v77, v240
	v_mul_f32_e32 v76, v74, v78
	v_cvt_pk_bf16_f32 v75, v75, v76
	v_and_b32_e32 v80, 0xffff0000, v44
	s_nop 1
	v_mov_b32_dpp v241, v75 quad_perm:[1,0,3,2] row_mask:0xf bank_mask:0xf
	v_perm_b32 v241, v241, v75, v239
	ds_write_b32 v77, v241 offset:544
	v_mul_f32_e32 v75, v74, v79
	v_lshlrev_b32_e32 v81, 16, v45
	v_and_b32_e32 v82, 0xffff0000, v45
	v_mul_f32_e32 v76, v74, v80
	v_cvt_pk_bf16_f32 v75, v75, v76
	s_nop 1
	v_mov_b32_dpp v242, v75 quad_perm:[1,0,3,2] row_mask:0xf bank_mask:0xf
	v_perm_b32 v242, v242, v75, v239
	ds_write_b32 v77, v242 offset:1088
	v_mul_f32_e32 v75, v74, v81
	v_mul_f32_e32 v76, v74, v82
	v_cvt_pk_bf16_f32 v75, v75, v76
	v_cndmask_b32_e64 v76, 0, 1, s[0:1]
	v_cmp_ne_u32_e64 s[72:73], 1, v76
	s_andn2_b64 vcc, exec, s[0:1]
	s_nop 1
	v_mov_b32_dpp v243, v75 quad_perm:[1,0,3,2] row_mask:0xf bank_mask:0xf
	v_perm_b32 v243, v243, v75, v239
	ds_write_b32 v77, v243 offset:1632
	s_cbranch_vccnz .LBB0_432
	v_add_u32_e32 v75, s20, v147
	ds_write_b128 v75, v[46:49] offset:34816
; #define PG8_LAS __attribute__((address_space(3)))
; __device__ __forceinline__ unsigned pk2(float lo, float hi) { return pg8::cvt_pk_bf16(lo, hi); }
; __device__ __forceinline__ void unpack8(const u32x4 r, float (&o)[8]) { o[0] = bflo(r.x); o[1] = bfhi(r.x); o[2] = bflo(r.y); o[3] = bfhi(r.y); o[4] = bflo(r.z); o[5] = bfhi(r.z); o[6] = bflo(r.w); o[7] = bfhi(r.w); }
; __device__ __forceinline__ void phase_ssd_mfma(const Params& p, unsigned char* smem) {
;     ...
;             for (int j = 0; j < 4; ++j) { const int n0 = 8 * (q4 + 4 * j); const u32x4 v = bv[j];
;                 if (!isctx) *(PG8_LAS u32x4*)(L + SS_B + sm * SS_LD + n0 * 2) = v;
;                 float f[8]; unpack8(v, f);
;                 PG8_LAS unsigned char* d = L + SS_BT + n0 * SS_LD + sm * 2;
; #pragma unroll
;                 for (int e = 0; e < 8; e += 2) { const unsigned w2 = pk2(f[e] * wsc, f[e + 1] * wsc);
;                     *(PG8_LAS unsigned short*)(d + e * SS_LD) = (unsigned short)(w2 & 0xffffu); *(PG8_LAS unsigned short*)(d + (e + 1) * SS_LD) = (unsigned short)(w2 >> 16); } }
;             if (!isctx) {
; #pragma unroll
;                 for (int j = 0; j < 4; ++j) *(PG8_LAS u32x4*)(L + SS_C + ((tid >> 4) + 32 * j) * SS_LD + (tid & 15) * 16) = cv[j];
.LBB0_432:
	v_lshlrev_b32_e32 v75, 16, v46
	v_and_b32_e32 v76, 0xffff0000, v46
	v_mul_f32_e32 v75, v74, v75
	v_mul_f32_e32 v76, v74, v76
	v_lshlrev_b32_e32 v77, 16, v47
	v_cvt_pk_bf16_f32 v76, v75, v76
	v_add_u32_e32 v75, s90, v238
	v_and_b32_e32 v78, 0xffff0000, v47
	s_nop 1
	v_mov_b32_dpp v240, v76 quad_perm:[1,0,3,2] row_mask:0xf bank_mask:0xf
	v_perm_b32 v240, v240, v76, v239
	ds_write_b32 v75, v240
	v_mul_f32_e32 v76, v74, v77
	v_lshlrev_b32_e32 v79, 16, v48
	v_mul_f32_e32 v77, v74, v78
	v_cvt_pk_bf16_f32 v76, v76, v77
	v_and_b32_e32 v80, 0xffff0000, v48
	s_nop 1
	v_mov_b32_dpp v241, v76 quad_perm:[1,0,3,2] row_mask:0xf bank_mask:0xf
	v_perm_b32 v241, v241, v76, v239
	ds_write_b32 v75, v241 offset:544
	v_mul_f32_e32 v76, v74, v79
	v_lshlrev_b32_e32 v81, 16, v49
	v_mul_f32_e32 v77, v74, v80
	v_cvt_pk_bf16_f32 v76, v76, v77
	v_and_b32_e32 v82, 0xffff0000, v49
	s_nop 1
	v_mov_b32_dpp v242, v76 quad_perm:[1,0,3,2] row_mask:0xf bank_mask:0xf
	v_perm_b32 v242, v242, v76, v239
	ds_write_b32 v75, v242 offset:1088
	v_mul_f32_e32 v76, v74, v81
	s_and_b64 vcc, exec, s[72:73]
	v_mul_f32_e32 v77, v74, v82
	v_cvt_pk_bf16_f32 v76, v76, v77
	s_nop 1
	v_mov_b32_dpp v243, v76 quad_perm:[1,0,3,2] row_mask:0xf bank_mask:0xf
	v_perm_b32 v243, v243, v76, v239
	ds_write_b32 v75, v243 offset:1632
	s_cbranch_vccnz .LBB0_434
	v_add_u32_e32 v76, s21, v147
	ds_write_b128 v76, v[50:53] offset:34816
.LBB0_434:
	v_lshlrev_b32_e32 v76, 16, v50
	v_and_b32_e32 v77, 0xffff0000, v50
	v_mul_f32_e32 v76, v74, v76
	v_lshlrev_b32_e32 v78, 16, v51
	v_mul_f32_e32 v77, v74, v77
	v_cvt_pk_bf16_f32 v76, v76, v77
	v_and_b32_e32 v79, 0xffff0000, v51
	s_nop 1
	v_mov_b32_dpp v240, v76 quad_perm:[1,0,3,2] row_mask:0xf bank_mask:0xf
	v_perm_b32 v240, v240, v76, v239
	ds_write_b32 v75, v240 offset:8704
	v_mul_f32_e32 v76, v74, v78
	v_lshlrev_b32_e32 v80, 16, v52
	v_mul_f32_e32 v77, v74, v79
	v_cvt_pk_bf16_f32 v76, v76, v77
	v_and_b32_e32 v81, 0xffff0000, v52
	s_nop 1
	v_mov_b32_dpp v241, v76 quad_perm:[1,0,3,2] row_mask:0xf bank_mask:0xf
	v_perm_b32 v241, v241, v76, v239
	ds_write_b32 v75, v241 offset:9248
	v_mul_f32_e32 v76, v74, v80
	v_lshlrev_b32_e32 v82, 16, v53
	v_mul_f32_e32 v77, v74, v81
	v_cvt_pk_bf16_f32 v76, v76, v77
	v_and_b32_e32 v83, 0xffff0000, v53
	s_nop 1
	v_mov_b32_dpp v242, v76 quad_perm:[1,0,3,2] row_mask:0xf bank_mask:0xf
	v_perm_b32 v242, v242, v76, v239
	ds_write_b32 v75, v242 offset:9792
	v_mul_f32_e32 v76, v74, v82
	s_and_b64 vcc, exec, s[72:73]
	v_mul_f32_e32 v77, v74, v83
	v_cvt_pk_bf16_f32 v76, v76, v77
	s_nop 1
	v_mov_b32_dpp v243, v76 quad_perm:[1,0,3,2] row_mask:0xf bank_mask:0xf
	v_perm_b32 v243, v243, v76, v239
	ds_write_b32 v75, v243 offset:10336
	s_cbranch_vccnz .LBB0_436
	v_add_u32_e32 v76, s22, v147
	s_waitcnt vmcnt(0)
	ds_write_b128 v76, v[54:57] offset:34816
.LBB0_436:
	s_waitcnt vmcnt(0)
	v_lshlrev_b32_e32 v76, 16, v54
	v_and_b32_e32 v77, 0xffff0000, v54
	v_mul_f32_e32 v76, v74, v76
	v_lshlrev_b32_e32 v78, 16, v55
	v_mul_f32_e32 v77, v74, v77
	v_cvt_pk_bf16_f32 v76, v76, v77
	v_and_b32_e32 v79, 0xffff0000, v55
	s_nop 1
	v_mov_b32_dpp v240, v76 quad_perm:[1,0,3,2] row_mask:0xf bank_mask:0xf
	v_perm_b32 v240, v240, v76, v239
	ds_write_b32 v75, v240 offset:17408
	v_mul_f32_e32 v76, v74, v78
	v_lshlrev_b32_e32 v80, 16, v56
	v_mul_f32_e32 v77, v74, v79
	v_cvt_pk_bf16_f32 v76, v76, v77
	v_and_b32_e32 v81, 0xffff0000, v56
	s_nop 1
	v_mov_b32_dpp v241, v76 quad_perm:[1,0,3,2] row_mask:0xf bank_mask:0xf
	v_perm_b32 v241, v241, v76, v239
	ds_write_b32 v75, v241 offset:17952
	v_mul_f32_e32 v76, v74, v80
	v_lshlrev_b32_e32 v82, 16, v57
	v_and_b32_e32 v83, 0xffff0000, v57
	v_mul_f32_e32 v77, v74, v81
	v_cvt_pk_bf16_f32 v76, v76, v77
	s_nop 1
	v_mov_b32_dpp v242, v76 quad_perm:[1,0,3,2] row_mask:0xf bank_mask:0xf
	v_perm_b32 v242, v242, v76, v239
	ds_write_b32 v75, v242 offset:18496
	v_mul_f32_e32 v76, v74, v82
	v_mul_f32_e32 v74, v74, v83
	v_cvt_pk_bf16_f32 v74, v76, v74
	s_and_b64 vcc, exec, s[0:1]
	s_nop 1
	v_mov_b32_dpp v243, v74 quad_perm:[1,0,3,2] row_mask:0xf bank_mask:0xf
	v_perm_b32 v243, v243, v74, v239
	ds_write_b32 v75, v243 offset:19040
	s_cbranch_vccz .LBB0_438
	ds_write_b128 v185, v[10:13]
	ds_write_b128 v185, v[22:25] offset:8704
	ds_write_b128 v185, v[26:29] offset:17408
	ds_write_b128 v185, v[30:33] offset:26112
